# preparation on 208 workgroups (was 171)
# speedup vs baseline: 1.0203x; 1.0203x over previous
; __device__ __forceinline__ void p2_rwkv_prep(const Params& P, float* lds) {
;     const int tid = threadIdx.x, lane = tid & 63, wave = tid >> 6;
;     const bf16_t* prw = (const bf16_t*)(P.ws + WS_PRW);
;     float* RSB = (float*)(P.ws + WS_RSB);
;     constexpr int CT = 8, NCHK = NTK / CT;
;     float* xbuf = lds;
;     float* yt = lds + 2 * CT * 128 + wave * (2 * CT * 64);
;     float* ot = lds + 2 * CT * 128 + 8 * (2 * CT * 64) + wave * 768;
;     prep_bf16x8 wbh[2][4][2], wbl[2][4][2];
;     float w0c = 0.f, a0c = 0.f, kkc = 0.f, kac = 0.f, rkc = 0.f, mur = 0.f, muk = 0.f, muv = 0.f, mux = 0.f;
;     if (tid < RW) {
;         const prep_bf16x8* LF = (const prep_bf16x8*)(P.ws + WS_LFRAG);
; #pragma unroll
;         for (int mt = 0; mt < 2; ++mt)
; #pragma unroll
;             for (int nt = 0; nt < 4; ++nt)
; #pragma unroll
;                 for (int s = 0; s < 2; ++s) { const int fi = (((mt * 6 + wave) * 4 + nt) * 2 + s) * 64 + lane; wbh[mt][nt][s] = LF[fi]; wbl[mt][nt][s] = LF[2 * 6 * 4 * 2 * 64 + fi]; }
;         w0c = P.w0[tid]; a0c = P.a0[tid]; kkc = P.k_k[tid]; kac = P.k_a[tid]; rkc = P.r_k[tid];
;         mur = P.mu_shift[tid]; muk = P.mu_shift[RW + tid]; muv = P.mu_shift[2 * RW + tid];
;     } else {
; #pragma unroll
;         for (int mt = 0; mt < 2; ++mt)
; #pragma unroll
;             for (int nt = 0; nt < 4; ++nt)
; #pragma unroll
;                 for (int s = 0; s < 2; ++s)
; #pragma unroll
;                     for (int j = 0; j < 8; ++j) { wbh[mt][nt][s][j] = 0; wbl[mt][nt][s][j] = 0; }
;         mux = P.mu_shift[1152 + (tid - RW)];
;     }
;     int ch = blockIdx.x;
;     if (tid >= RW && ch < NCHK) prep_produce(P, prw, ch, xbuf, tid - RW, mux);
; __global__ void __launch_bounds__(512, 2) mk_fwd(Params P) {
;     ...
;     if (IN(2)) {
;         if (blockIdx.x < NPREP) {
;             p2_rwkv_prep(P, ldsf);
.LBB0_699:
	s_cmp_lt_i32 s60, 3
	s_cselect_b64 s[2:3], -1, 0
	s_and_b64 s[0:1], s[2:3], s[0:1]
	s_andn2_b64 vcc, exec, s[0:1]
	s_cbranch_vccnz .LBB0_939
	s_cmpk_gt_u32 s56, 0xcf
	s_cbranch_scc1 .LBB0_905
	s_movk_i32 s0, 0x180
	v_cmp_gt_u32_e64 s[4:5], s0, v0
	s_movk_i32 s0, 0x17f
	v_cmp_lt_u32_e32 vcc, s0, v0
	s_and_saveexec_b64 s[0:1], vcc
	s_xor_b64 s[0:1], exec, s[0:1]
	s_cbranch_execz .LBB0_703
	v_readlane_b32 s8, v252, 16
	v_lshlrev_b32_e32 v1, 2, v0
	v_readlane_b32 s18, v252, 26
	v_readlane_b32 s19, v252, 27
	v_readlane_b32 s9, v252, 17
	v_readlane_b32 s10, v252, 18
	v_readlane_b32 s11, v252, 19
	v_readlane_b32 s12, v252, 20
	v_readlane_b32 s13, v252, 21
	global_load_dword v173, v1, s[18:19] offset:3072
	v_readlane_b32 s14, v252, 22
	v_readlane_b32 s15, v252, 23
	v_readlane_b32 s16, v252, 24
	v_readlane_b32 s17, v252, 25
	v_readlane_b32 s20, v252, 28
	v_readlane_b32 s21, v252, 29
	v_readlane_b32 s22, v252, 30
	v_readlane_b32 s23, v252, 31

; __device__ __forceinline__ float bf2f(bf16_t b) { return __uint_as_float(((unsigned)b) << 16); }
; __device__ __forceinline__ void p2_rwkv_prep(const Params& P, float* lds) {
;     ...
;     int ch = blockIdx.x;
;     if (tid >= RW && ch < NCHK) prep_produce(P, prw, ch, xbuf, tid - RW, mux);
;     for (int it = 0; ch < NCHK; ch += NPREP, ++it) {
;         const int tok0 = ch * CT;
;         float* bufc = xbuf + (it & 1) * (CT * 128); float* bufn = xbuf + ((it + 1) & 1) * (CT * 128);
;         float nr[4], nk[4], nv[4], qr = 0.f, qk = 0.f, qv = 0.f;
;         if (tid < RW) {
; #pragma unroll
;             for (int q = 0; q < 4; ++q) { const bf16_t* p = prw + (size_t)(tok0 + q) * RCOLS + tid; nr[q] = bf2f(p[0]); nk[q] = bf2f(p[RW]); nv[q] = bf2f(p[2 * RW]); }
;             if (tok0 < NTOK && (tok0 & (SEQ - 1))) { const bf16_t* p = prw + (size_t)(tok0 - 1) * RCOLS + tid; qr = bf2f(p[0]); qk = bf2f(p[RW]); qv = bf2f(p[2 * RW]); }
;         }
.LBB0_760:
	s_or_b64 exec, exec, s[2:3]
	v_lshl_add_u32 v130, v170, 12, 0
	v_lshlrev_b32_e32 v132, 1, v0
	v_mov_b32_e32 v133, 0
	v_lshlrev_b32_e32 v134, 9, v0
	v_lshlrev_b32_e32 v172, 2, v1
	v_lshlrev_b32_e32 v131, 10, v170
	v_lshl_add_u64 v[176:177], s[0:1], 0, v[132:133]
	v_and_b32_e32 v134, 0xe00, v134
	v_and_b32_e32 v132, 0x60, v132
	v_add_u32_e32 v199, v130, v172
	s_load_dwordx16 s[36:51], s[58:59], 0x0
	v_add3_u32 v198, 0, v134, v132
	v_and_b32_e32 v132, 8, v0
	v_sub_u32_e32 v200, v199, v131
	v_cmp_eq_u32_e64 s[8:9], 0, v132
	v_and_b32_e32 v132, 15, v0
	v_mad_u32_u24 v131, v1, 12, v200
	s_add_u32 s18, s78, 0xa2d4000
	v_lshl_add_u32 v134, v132, 2, v130
	v_lshlrev_b32_e32 v130, 6, v0
	v_mad_i32_i24 v203, v1, -12, v131
	s_addc_u32 s19, s79, 0
	v_cmp_gt_u32_e64 s[10:11], 32, v1
	v_cmp_eq_u32_e64 s[12:13], 0, v1
	v_and_b32_e32 v130, 0x400, v130
	v_mad_u32_u24 v1, v1, 12, v203
	v_lshlrev_b32_e32 v132, 2, v0
	v_lshl_add_u64 v[180:181], v[174:175], 1, s[0:1]
	s_lshl_b32 s0, s56, 3
	v_mov_b32_e32 v171, v133
	v_cmp_gt_u32_e64 s[14:15], 64, v174
	s_movk_i32 s22, 0x400
	v_add_u32_e32 v201, 0xa000, v131
	v_add_u32_e32 v202, 0xa400, v131
	v_add_u32_e32 v204, 0xa600, v1
	v_add_u32_e32 v205, 0xaa00, v1
	v_lshl_add_u32 v206, v174, 2, 0
	s_waitcnt lgkmcnt(0)
	v_lshl_add_u64 v[178:179], s[50:51], 0, v[132:133]
	s_add_i32 s23, s0, 0x687
	s_mov_b32 s24, 0x3fb8aa3b
	s_movk_i32 s25, 0x610
	s_mov_b32 s26, 0x3f200000
	s_mov_b32 s27, 0xc2ce8ed0
	s_mov_b32 s28, 0x42b17218
	v_mov_b32_e32 v207, 0x3ca908c9
	s_brev_b32 s29, -2
	v_mov_b32_e32 v208, 0xa00
	v_add_u32_e32 v209, v134, v130
	v_mov_b32_e32 v210, 0x1400
	v_mov_b32_e32 v211, 0x610
	v_mov_b32_e32 v212, 0x7f800000
	s_mov_b32 s30, s56
	s_branch .LBB0_764

; __device__ __forceinline__ float bf2f(bf16_t b) { return __uint_as_float(((unsigned)b) << 16); }
; __device__ __forceinline__ void p2_rwkv_prep(const Params& P, float* lds) {
;     ...
;     for (int it = 0; ch < NCHK; ch += NPREP, ++it) {
;         const int tok0 = ch * CT;
;         float* bufc = xbuf + (it & 1) * (CT * 128); float* bufn = xbuf + ((it + 1) & 1) * (CT * 128);
;         float nr[4], nk[4], nv[4], qr = 0.f, qk = 0.f, qv = 0.f;
;         if (tid < RW) {
; #pragma unroll
;             for (int q = 0; q < 4; ++q) { const bf16_t* p = prw + (size_t)(tok0 + q) * RCOLS + tid; nr[q] = bf2f(p[0]); nk[q] = bf2f(p[RW]); nv[q] = bf2f(p[2 * RW]); }
;             if (tok0 < NTOK && (tok0 & (SEQ - 1))) { const bf16_t* p = prw + (size_t)(tok0 - 1) * RCOLS + tid; qr = bf2f(p[0]); qk = bf2f(p[RW]); qv = bf2f(p[2 * RW]); }
;         }
.LBB0_763:
	s_or_b64 exec, exec, s[0:1]
	s_add_i32 s0, s30, 0xd0
	s_addk_i32 s23, 0x680
	s_addk_i32 s22, 0x400
	s_cmpk_lt_i32 s30, 0x734
	s_mov_b32 s30, s0
	s_cbranch_scc0 .LBB0_901
.LBB0_764:
	s_cmpk_gt_i32 s30, 0x7ff
	s_cselect_b64 s[98:99], -1, 0
	v_mov_b32_e32 v255, 1.0
	s_add_i32 s31, s23, 0xfffff979
	v_mov_b32_e32 v131, 0
	v_mov_b32_e32 v130, 0
	v_mov_b32_e32 v1, 0
	s_and_saveexec_b64 s[0:1], s[4:5]
	s_cbranch_execz .LBB0_768
	v_mad_u64_u32 v[130:131], s[2:3], s31, v208, v[176:177]
	s_add_i32 s2, s23, 0xfffff97a
	s_nop 0
	v_mad_u64_u32 v[134:135], s[2:3], s2, v208, v[176:177]
	s_add_i32 s2, s23, 0xfffff97b
	s_nop 0
	v_mad_u64_u32 v[146:147], s[2:3], s2, v208, v[176:177]
	global_load_ushort v141, v[130:131], off
	global_load_ushort v144, v[130:131], off offset:768
	global_load_ushort v139, v[134:135], off
	global_load_ushort v142, v[134:135], off offset:768
	s_nop 0
	global_load_ushort v135, v[134:135], off offset:1536
	s_nop 0
	global_load_ushort v134, v[146:147], off
	global_load_ushort v138, v[146:147], off offset:768
	global_load_ushort v143, v[130:131], off offset:1536
	s_add_i32 s2, s23, 0xfffff97c
	v_mad_u64_u32 v[130:131], s[2:3], s2, v208, v[176:177]
	global_load_ushort v136, v[130:131], off
	global_load_ushort v140, v[130:131], off offset:768
	global_load_ushort v132, v[130:131], off offset:1536
	global_load_ushort v137, v[146:147], off offset:1536
	s_cmpk_gt_i32 s30, 0x7ff
	s_cselect_b64 s[2:3], -1, 0
	s_and_b32 s16, s30, 0x1ff
	s_cmp_eq_u32 s16, 0
	s_cselect_b64 s[16:17], -1, 0
	s_or_b64 s[2:3], s[2:3], s[16:17]
	v_mov_b32_e32 v1, 0
	s_and_b64 vcc, exec, s[2:3]
	v_mov_b32_e32 v130, 0
	v_mov_b32_e32 v131, 0
	s_cbranch_vccnz .LBB0_767
	s_add_i32 s2, s23, 0xfffff978
	v_mad_i64_i32 v[130:131], s[2:3], s2, v208, v[176:177]
	global_load_ushort v1, v[130:131], off
	global_load_ushort v145, v[130:131], off offset:1536
	global_load_ushort v146, v[130:131], off offset:768
	s_waitcnt vmcnt(0)
	v_lshlrev_b32_e32 v131, 16, v1
	v_lshlrev_b32_e32 v130, 16, v145
	v_lshlrev_b32_e32 v1, 16, v146

; __device__ __forceinline__ float bf2f(bf16_t b) { return __uint_as_float(((unsigned)b) << 16); }
; __device__ __forceinline__ float sigmoidf_(float x) { return 1.f / (1.f + __expf(-x)); }
; __device__ __forceinline__ void p2_rwkv_prep(const Params& P, float* lds) {
;     ...
;             for (int tk = tg; tk < tg + 4; ++tk) {
;                 const int tok = tok0 + tk;
;                 if (tok >= NTOK) { const float* p = P.state_shift + (size_t)(tok - NTOK) * RCOLS + tid; qr = p[0]; qk = p[RW]; qv = p[2 * RW]; }
;                 const float cr = nr[tk & 3], ck = nk[tk & 3], cv = nv[tk & 3];
;                 if (tk + 4 < CT) { const bf16_t* p = prw + (size_t)(tok + 4) * RCOLS + tid; nr[tk & 3] = bf2f(p[0]); nk[tk & 3] = bf2f(p[RW]); nv[tk & 3] = bf2f(p[2 * RW]); }
;                 const float r = cr + (qr - cr) * mur, kraw = ck + (qk - ck) * muk, v = cv + (qv - cv) * muv;
;                 qr = cr; qk = ck; qv = cv;
;                 const float aw = w0c + yt[tk * 64 + cc], aa = a0c + yt[(CT + tk) * 64 + cc];
;                 const float w = __expf(-DECAY_SCALE * sigmoidf_(aw)), a = sigmoidf_(aa);
;                 const float kkv = kraw * kkc;
;                 const float n2 = wave_sum_fast(kkv * kkv);
;                 const float kk = kkv * rsqrtf(fmaxf(n2, 1e-12f));
;                 const float kmod = kraw * (1.f + (a - 1.f) * kac);
;                 const float bb = kk * a;
;                 const float br = wave_sum_fast(bb * r);
;                 ekk[tk - tg] = kk; ew[tk - tg] = w; ebb[tk - tg] = bb; ekm[tk - tg] = kmod; ewr[tk - tg] = w * r - kk * br; ev[tk - tg] = v;
;                 ebr[tk - tg] = br; ekr[tk - tg] = wave_sum_fast(kmod * r); erk[tk - tg] = wave_sum_fast(r * kmod * rkc);
.LBB0_785:
	s_or_b64 exec, exec, s[2:3]
	s_waitcnt lgkmcnt(0)
	s_cmpk_gt_i32 s30, 0x7ff
	s_cselect_b64 s[2:3], -1, 0
	s_cmpk_lt_i32 s30, 0x800
	s_cbranch_scc1 .LBB0_787
	s_add_i32 s16, s23, 0xffffb979
	v_mad_u64_u32 v[134:135], s[16:17], s16, v210, v[178:179]
	global_load_dword v131, v[134:135], off
	global_load_dword v1, v[134:135], off offset:1536
	global_load_dword v130, v[134:135], off offset:3072
.LBB0_787:
	s_add_i32 s16, s23, 0xfffff97d
	v_mad_u64_u32 v[136:137], s[20:21], s16, v208, v[176:177]
	ds_read2st64_b32 v[134:135], v199 offset0:32 offset1:40
	global_load_ushort v156, v[136:137], off
	global_load_ushort v158, v[136:137], off offset:768
	global_load_ushort v157, v[136:137], off offset:1536
	s_waitcnt vmcnt(5)
	v_sub_f32_e32 v131, v131, v188
	v_fma_f32 v152, v196, v131, v188
	s_waitcnt vmcnt(4)
	v_sub_f32_e32 v1, v1, v189
	s_waitcnt lgkmcnt(0)
	v_add_f32_e32 v132, v194, v135
	v_mul_f32_e32 v132, 0xbfb8aa3b, v132
	v_exp_f32_e32 v132, v132
	v_mov_b32_e32 v136, v189
	v_fmac_f32_e32 v136, v195, v1
	v_mov_b32_e32 v167, v213
	v_add_f32_e32 v131, 1.0, v132
	v_div_scale_f32 v132, s[20:21], v131, v131, 1.0
	v_rcp_f32_e32 v135, v132
	s_nop 0
	v_fma_f32 v1, -v132, v135, 1.0
	v_fmac_f32_e32 v135, v1, v135
	v_div_scale_f32 v1, vcc, 1.0, v131, 1.0
	v_mul_f32_e32 v137, v1, v135
	v_fma_f32 v138, -v132, v137, v1
	v_fmac_f32_e32 v137, v138, v135
	v_fma_f32 v1, -v132, v137, v1
	v_mul_f32_e32 v132, v193, v136
	v_mul_f32_e32 v138, v132, v132
	v_div_fmas_f32 v1, v1, v135, v137
	v_div_fixup_f32 v1, v1, v131, 1.0
	v_mov_b32_dpp v138, v138 quad_perm:[1,0,3,2] row_mask:0xf bank_mask:0xf bound_ctrl:1
	v_fmac_f32_e32 v138, v132, v132
	v_add_f32_e32 v131, -1.0, v1
	v_fma_f32 v131, v192, v131, 1.0
	v_add_f32_dpp v138, v138, v138 quad_perm:[2,3,0,1] row_mask:0xf bank_mask:0xf bound_ctrl:1
	v_mul_f32_e32 v154, v136, v131
	s_andn2_b64 vcc, exec, s[2:3]
	v_add_f32_dpp v138, v138, v138 row_ror:4 row_mask:0xf bank_mask:0xf bound_ctrl:1
	s_nop 1
	v_add_f32_dpp v138, v138, v138 row_ror:8 row_mask:0xf bank_mask:0xf bound_ctrl:1
	v_mov_b32_e32 v139, v138
	s_nop 1
	v_permlane16_swap_b32_e32 v138, v139
	v_add_f32_e32 v138, v138, v139
	v_mov_b32_e32 v139, v138
	s_nop 1
	v_permlane32_swap_b32_e32 v138, v139
	v_add_f32_e32 v138, v138, v139
	v_max_f32_e32 v138, 0x2b8cbccc, v138
	v_rsq_f32_e32 v138, v138
	s_nop 0
	v_mul_f32_e32 v132, v132, v138
	v_mul_f32_e32 v155, v1, v132
	v_mul_f32_e32 v1, v152, v155
	s_nop 1
	v_mov_b32_dpp v1, v1 quad_perm:[1,0,3,2] row_mask:0xf bank_mask:0xf bound_ctrl:1
	v_fmac_f32_e32 v1, v152, v155
	s_nop 1
	v_add_f32_dpp v1, v1, v1 quad_perm:[2,3,0,1] row_mask:0xf bank_mask:0xf bound_ctrl:1
	s_nop 1
	v_add_f32_dpp v1, v1, v1 row_ror:4 row_mask:0xf bank_mask:0xf bound_ctrl:1
	s_nop 1
	v_add_f32_dpp v1, v1, v1 row_ror:8 row_mask:0xf bank_mask:0xf bound_ctrl:1
	v_mov_b32_e32 v131, v1
	s_nop 1
	v_permlane16_swap_b32_e32 v1, v131
	v_add_f32_e32 v136, v1, v131
	v_mul_f32_e32 v1, v152, v154
	v_mov_b32_e32 v150, v136
	s_nop 1
	v_permlane32_swap_b32_e32 v136, v150
	v_mov_b32_dpp v131, v1 quad_perm:[1,0,3,2] row_mask:0xf bank_mask:0xf bound_ctrl:1
	v_fmac_f32_e32 v131, v152, v154
	s_nop 1
	v_add_f32_dpp v131, v131, v131 quad_perm:[2,3,0,1] row_mask:0xf bank_mask:0xf bound_ctrl:1
	s_nop 1
	v_add_f32_dpp v131, v131, v131 row_ror:4 row_mask:0xf bank_mask:0xf bound_ctrl:1
	s_nop 1
	v_add_f32_dpp v131, v131, v131 row_ror:8 row_mask:0xf bank_mask:0xf bound_ctrl:1
	v_mov_b32_e32 v135, v131
	s_nop 1
	v_permlane16_swap_b32_e32 v131, v135
	v_add_f32_e32 v137, v131, v135
	v_mul_f32_e32 v131, v197, v1
	v_mov_b32_e32 v151, v137
	s_nop 1
	v_permlane32_swap_b32_e32 v137, v151
	v_mov_b32_dpp v131, v131 quad_perm:[1,0,3,2] row_mask:0xf bank_mask:0xf bound_ctrl:1
	v_fmac_f32_e32 v131, v197, v1
	s_nop 1
	v_add_f32_dpp v1, v131, v131 quad_perm:[2,3,0,1] row_mask:0xf bank_mask:0xf bound_ctrl:1
	s_nop 1
	v_add_f32_dpp v1, v1, v1 row_ror:4 row_mask:0xf bank_mask:0xf bound_ctrl:1
	s_nop 1
	v_add_f32_dpp v1, v1, v1 row_ror:8 row_mask:0xf bank_mask:0xf bound_ctrl:1
	v_mov_b32_e32 v131, v1
	s_nop 1
	v_permlane16_swap_b32_e32 v1, v131
	v_add_f32_e32 v168, v1, v131
	v_mov_b32_e32 v169, v168
	s_nop 1
	v_permlane32_swap_b32_e32 v168, v169
	s_cbranch_vccnz .LBB0_789
	s_add_i32 s2, s23, 0xffffb97a
	v_mad_u64_u32 v[138:139], s[2:3], s2, v210, v[178:179]
	global_load_dword v188, v[138:139], off
	global_load_dword v189, v[138:139], off offset:1536
	global_load_dword v167, v[138:139], off offset:3072
; __device__ __forceinline__ float bf2f(bf16_t b) { return __uint_as_float(((unsigned)b) << 16); }
; __device__ __forceinline__ float sigmoidf_(float x) { return 1.f / (1.f + __expf(-x)); }
; __device__ __forceinline__ void p2_rwkv_prep(const Params& P, float* lds) {
;     ...
;             for (int tk = tg; tk < tg + 4; ++tk) {
;                 const int tok = tok0 + tk;
;                 if (tok >= NTOK) { const float* p = P.state_shift + (size_t)(tok - NTOK) * RCOLS + tid; qr = p[0]; qk = p[RW]; qv = p[2 * RW]; }
;                 const float cr = nr[tk & 3], ck = nk[tk & 3], cv = nv[tk & 3];
;                 if (tk + 4 < CT) { const bf16_t* p = prw + (size_t)(tok + 4) * RCOLS + tid; nr[tk & 3] = bf2f(p[0]); nk[tk & 3] = bf2f(p[RW]); nv[tk & 3] = bf2f(p[2 * RW]); }
;                 const float r = cr + (qr - cr) * mur, kraw = ck + (qk - ck) * muk, v = cv + (qv - cv) * muv;
;                 qr = cr; qk = ck; qv = cv;
;                 const float aw = w0c + yt[tk * 64 + cc], aa = a0c + yt[(CT + tk) * 64 + cc];
;                 const float w = __expf(-DECAY_SCALE * sigmoidf_(aw)), a = sigmoidf_(aa);
;                 const float kkv = kraw * kkc;
;                 const float n2 = wave_sum_fast(kkv * kkv);
;                 const float kk = kkv * rsqrtf(fmaxf(n2, 1e-12f));
;                 const float kmod = kraw * (1.f + (a - 1.f) * kac);
;                 const float bb = kk * a;
;                 const float br = wave_sum_fast(bb * r);
;                 ekk[tk - tg] = kk; ew[tk - tg] = w; ebb[tk - tg] = bb; ekm[tk - tg] = kmod; ewr[tk - tg] = w * r - kk * br; ev[tk - tg] = v;
;                 ebr[tk - tg] = br; ekr[tk - tg] = wave_sum_fast(kmod * r); erk[tk - tg] = wave_sum_fast(r * kmod * rkc);
.LBB0_789:
	s_add_i32 s17, s23, 0xfffff97e
	v_mad_u64_u32 v[140:141], s[2:3], s17, v208, v[176:177]
	ds_read2st64_b32 v[138:139], v199 offset0:33 offset1:41
	global_load_ushort v159, v[140:141], off
	global_load_ushort v161, v[140:141], off offset:768
	global_load_ushort v160, v[140:141], off offset:1536
	s_waitcnt vmcnt(5)
	v_sub_f32_e32 v131, v188, v186
	s_waitcnt vmcnt(4)
	v_sub_f32_e32 v140, v189, v187
	v_mov_b32_e32 v141, v187
	s_waitcnt lgkmcnt(0)
	v_add_f32_e32 v1, v194, v139
	v_mul_f32_e32 v1, 0xbfb8aa3b, v1
	v_exp_f32_e32 v1, v1
	v_fma_f32 v139, v196, v131, v186
	v_fmac_f32_e32 v141, v195, v140
	s_add_i32 s33, s23, 0xfffff97b
	v_add_f32_e32 v1, 1.0, v1
	v_div_scale_f32 v131, s[2:3], v1, v1, 1.0
	v_rcp_f32_e32 v135, v131
	s_cmpk_lt_i32 s33, 0x4000
	v_mov_b32_e32 v218, v214
	v_fma_f32 v140, -v131, v135, 1.0
	v_fmac_f32_e32 v135, v140, v135
	v_div_scale_f32 v140, vcc, 1.0, v1, 1.0
	v_mul_f32_e32 v142, v140, v135
	v_fma_f32 v143, -v131, v142, v140
	v_fmac_f32_e32 v142, v143, v135
	v_fma_f32 v131, -v131, v142, v140
	v_mul_f32_e32 v140, v193, v141
	v_mul_f32_e32 v143, v140, v140
	v_div_fmas_f32 v131, v131, v135, v142
	v_div_fixup_f32 v1, v131, v1, 1.0
	v_mov_b32_dpp v143, v143 quad_perm:[1,0,3,2] row_mask:0xf bank_mask:0xf bound_ctrl:1
	v_fmac_f32_e32 v143, v140, v140
	v_add_f32_e32 v131, -1.0, v1
	v_fma_f32 v131, v192, v131, 1.0
	v_add_f32_dpp v143, v143, v143 quad_perm:[2,3,0,1] row_mask:0xf bank_mask:0xf bound_ctrl:1
	v_mul_f32_e32 v189, v141, v131
	s_nop 0
	v_add_f32_dpp v143, v143, v143 row_ror:4 row_mask:0xf bank_mask:0xf bound_ctrl:1
	s_nop 1
	v_add_f32_dpp v143, v143, v143 row_ror:8 row_mask:0xf bank_mask:0xf bound_ctrl:1
	v_mov_b32_e32 v144, v143
	s_nop 1
	v_permlane16_swap_b32_e32 v143, v144
	v_add_f32_e32 v143, v143, v144
	v_mov_b32_e32 v144, v143
	s_nop 1
	v_permlane32_swap_b32_e32 v143, v144
	v_add_f32_e32 v143, v143, v144
	v_max_f32_e32 v143, 0x2b8cbccc, v143
	v_rsq_f32_e32 v143, v143
	s_nop 0
	v_mul_f32_e32 v188, v140, v143
	v_mul_f32_e32 v217, v1, v188
	v_mul_f32_e32 v1, v139, v217
	s_nop 1
	v_mov_b32_dpp v1, v1 quad_perm:[1,0,3,2] row_mask:0xf bank_mask:0xf bound_ctrl:1
	v_fmac_f32_e32 v1, v139, v217
	s_nop 1
	v_add_f32_dpp v1, v1, v1 quad_perm:[2,3,0,1] row_mask:0xf bank_mask:0xf bound_ctrl:1
	s_nop 1
	v_add_f32_dpp v1, v1, v1 row_ror:4 row_mask:0xf bank_mask:0xf bound_ctrl:1
	s_nop 1
	v_add_f32_dpp v1, v1, v1 row_ror:8 row_mask:0xf bank_mask:0xf bound_ctrl:1
	v_mov_b32_e32 v131, v1
	s_nop 1
	v_permlane16_swap_b32_e32 v1, v131
	v_add_f32_e32 v142, v1, v131
	v_mul_f32_e32 v1, v139, v189
	v_mov_b32_e32 v144, v142
	s_nop 1
	v_permlane32_swap_b32_e32 v142, v144
	v_mov_b32_dpp v131, v1 quad_perm:[1,0,3,2] row_mask:0xf bank_mask:0xf bound_ctrl:1
	v_fmac_f32_e32 v131, v139, v189
	s_nop 1
	v_add_f32_dpp v131, v131, v131 quad_perm:[2,3,0,1] row_mask:0xf bank_mask:0xf bound_ctrl:1
	s_nop 1
	v_add_f32_dpp v131, v131, v131 row_ror:4 row_mask:0xf bank_mask:0xf bound_ctrl:1
	s_nop 1
	v_add_f32_dpp v131, v131, v131 row_ror:8 row_mask:0xf bank_mask:0xf bound_ctrl:1
	v_mov_b32_e32 v135, v131
	s_nop 1
	v_permlane16_swap_b32_e32 v131, v135
	v_add_f32_e32 v143, v131, v135
	v_mul_f32_e32 v131, v197, v1
	v_mov_b32_e32 v145, v143
	s_nop 1
	v_permlane32_swap_b32_e32 v143, v145
	v_mov_b32_dpp v131, v131 quad_perm:[1,0,3,2] row_mask:0xf bank_mask:0xf bound_ctrl:1
	v_fmac_f32_e32 v131, v197, v1
	s_nop 1
	v_add_f32_dpp v1, v131, v131 quad_perm:[2,3,0,1] row_mask:0xf bank_mask:0xf bound_ctrl:1
	s_nop 1
	v_add_f32_dpp v1, v1, v1 row_ror:4 row_mask:0xf bank_mask:0xf bound_ctrl:1
	s_nop 1
	v_add_f32_dpp v1, v1, v1 row_ror:8 row_mask:0xf bank_mask:0xf bound_ctrl:1
	v_mov_b32_e32 v131, v1
	s_nop 1
	v_permlane16_swap_b32_e32 v1, v131
	v_add_f32_e32 v219, v1, v131
	v_mov_b32_e32 v220, v219
	s_nop 1
	v_permlane32_swap_b32_e32 v219, v220
	s_cbranch_scc1 .LBB0_791
	s_add_i32 s2, s23, 0xffffb97b
	v_mad_u64_u32 v[140:141], s[2:3], s2, v210, v[178:179]
	global_load_dword v186, v[140:141], off
	global_load_dword v187, v[140:141], off offset:1536
	global_load_dword v218, v[140:141], off offset:3072
.LBB0_791:
	s_add_i32 s20, s23, 0xfffff97f
	v_mad_u64_u32 v[146:147], s[2:3], s20, v208, v[176:177]
	ds_read2st64_b32 v[140:141], v199 offset0:34 offset1:42
	global_load_ushort v162, v[146:147], off
	global_load_ushort v164, v[146:147], off offset:768
	global_load_ushort v163, v[146:147], off offset:1536
	s_waitcnt vmcnt(5)
	v_sub_f32_e32 v131, v186, v184
	s_waitcnt vmcnt(4)
	v_sub_f32_e32 v146, v187, v185
	v_mov_b32_e32 v147, v185
	s_waitcnt lgkmcnt(0)
; __device__ __forceinline__ float bf2f(bf16_t b) { return __uint_as_float(((unsigned)b) << 16); }
; __device__ __forceinline__ float sigmoidf_(float x) { return 1.f / (1.f + __expf(-x)); }
; __device__ __forceinline__ void p2_rwkv_prep(const Params& P, float* lds) {
;     ...
;             for (int tk = tg; tk < tg + 4; ++tk) {
;                 const int tok = tok0 + tk;
;                 if (tok >= NTOK) { const float* p = P.state_shift + (size_t)(tok - NTOK) * RCOLS + tid; qr = p[0]; qk = p[RW]; qv = p[2 * RW]; }
;                 const float cr = nr[tk & 3], ck = nk[tk & 3], cv = nv[tk & 3];
;                 if (tk + 4 < CT) { const bf16_t* p = prw + (size_t)(tok + 4) * RCOLS + tid; nr[tk & 3] = bf2f(p[0]); nk[tk & 3] = bf2f(p[RW]); nv[tk & 3] = bf2f(p[2 * RW]); }
;                 const float r = cr + (qr - cr) * mur, kraw = ck + (qk - ck) * muk, v = cv + (qv - cv) * muv;
;                 qr = cr; qk = ck; qv = cv;
;                 const float aw = w0c + yt[tk * 64 + cc], aa = a0c + yt[(CT + tk) * 64 + cc];
;                 const float w = __expf(-DECAY_SCALE * sigmoidf_(aw)), a = sigmoidf_(aa);
;                 const float kkv = kraw * kkc;
;                 const float n2 = wave_sum_fast(kkv * kkv);
;                 const float kk = kkv * rsqrtf(fmaxf(n2, 1e-12f));
;                 const float kmod = kraw * (1.f + (a - 1.f) * kac);
;                 const float bb = kk * a;
;                 const float br = wave_sum_fast(bb * r);
;                 ekk[tk - tg] = kk; ew[tk - tg] = w; ebb[tk - tg] = bb; ekm[tk - tg] = kmod; ewr[tk - tg] = w * r - kk * br; ev[tk - tg] = v;
;                 ebr[tk - tg] = br; ekr[tk - tg] = wave_sum_fast(kmod * r); erk[tk - tg] = wave_sum_fast(r * kmod * rkc);
	v_add_f32_e32 v1, v194, v141
	v_mul_f32_e32 v1, 0xbfb8aa3b, v1
	v_exp_f32_e32 v1, v1
	v_fma_f32 v141, v196, v131, v184
	v_fmac_f32_e32 v147, v195, v146
	s_add_i32 s34, s23, 0xfffff97c
	v_add_f32_e32 v1, 1.0, v1
	v_div_scale_f32 v131, s[2:3], v1, v1, 1.0
	v_rcp_f32_e32 v135, v131
	s_cmpk_lt_i32 s34, 0x4000
	v_mov_b32_e32 v222, v216
	v_fma_f32 v146, -v131, v135, 1.0
	v_fmac_f32_e32 v135, v146, v135
	v_div_scale_f32 v146, vcc, 1.0, v1, 1.0
	v_mul_f32_e32 v148, v146, v135
	v_fma_f32 v149, -v131, v148, v146
	v_fmac_f32_e32 v148, v149, v135
	v_fma_f32 v131, -v131, v148, v146
	v_mul_f32_e32 v146, v193, v147
	v_mul_f32_e32 v149, v146, v146
	v_div_fmas_f32 v131, v131, v135, v148
	v_div_fixup_f32 v1, v131, v1, 1.0
	v_mov_b32_dpp v149, v149 quad_perm:[1,0,3,2] row_mask:0xf bank_mask:0xf bound_ctrl:1
	v_fmac_f32_e32 v149, v146, v146
	v_add_f32_e32 v131, -1.0, v1
	v_fma_f32 v131, v192, v131, 1.0
	v_add_f32_dpp v149, v149, v149 quad_perm:[2,3,0,1] row_mask:0xf bank_mask:0xf bound_ctrl:1
	v_mul_f32_e32 v187, v147, v131
	s_nop 0
	v_add_f32_dpp v149, v149, v149 row_ror:4 row_mask:0xf bank_mask:0xf bound_ctrl:1
	s_nop 1
	v_add_f32_dpp v149, v149, v149 row_ror:8 row_mask:0xf bank_mask:0xf bound_ctrl:1
	v_mov_b32_e32 v153, v149
	s_nop 1
	v_permlane16_swap_b32_e32 v149, v153
	v_add_f32_e32 v149, v149, v153
	v_mov_b32_e32 v153, v149
	s_nop 1
	v_permlane32_swap_b32_e32 v149, v153
	v_add_f32_e32 v149, v149, v153
	v_max_f32_e32 v149, 0x2b8cbccc, v149
	v_rsq_f32_e32 v149, v149
	s_nop 0
	v_mul_f32_e32 v186, v146, v149
	v_mul_f32_e32 v221, v1, v186
	v_mul_f32_e32 v1, v141, v221
	s_nop 1
	v_mov_b32_dpp v1, v1 quad_perm:[1,0,3,2] row_mask:0xf bank_mask:0xf bound_ctrl:1
	v_fmac_f32_e32 v1, v141, v221
	s_nop 1
	v_add_f32_dpp v1, v1, v1 quad_perm:[2,3,0,1] row_mask:0xf bank_mask:0xf bound_ctrl:1
	s_nop 1
	v_add_f32_dpp v1, v1, v1 row_ror:4 row_mask:0xf bank_mask:0xf bound_ctrl:1
	s_nop 1
	v_add_f32_dpp v1, v1, v1 row_ror:8 row_mask:0xf bank_mask:0xf bound_ctrl:1
	v_mov_b32_e32 v131, v1
	s_nop 1
	v_permlane16_swap_b32_e32 v1, v131
	v_add_f32_e32 v146, v1, v131
	v_mul_f32_e32 v1, v141, v187
	v_mov_b32_e32 v148, v146
	s_nop 1
	v_permlane32_swap_b32_e32 v146, v148
	v_mov_b32_dpp v131, v1 quad_perm:[1,0,3,2] row_mask:0xf bank_mask:0xf bound_ctrl:1
	v_fmac_f32_e32 v131, v141, v187
	s_nop 1
	v_add_f32_dpp v131, v131, v131 quad_perm:[2,3,0,1] row_mask:0xf bank_mask:0xf bound_ctrl:1
	s_nop 1
	v_add_f32_dpp v131, v131, v131 row_ror:4 row_mask:0xf bank_mask:0xf bound_ctrl:1
	s_nop 1
	v_add_f32_dpp v131, v131, v131 row_ror:8 row_mask:0xf bank_mask:0xf bound_ctrl:1
	v_mov_b32_e32 v135, v131
	s_nop 1
	v_permlane16_swap_b32_e32 v131, v135
	v_add_f32_e32 v147, v131, v135
	v_mul_f32_e32 v131, v197, v1
	v_mov_b32_e32 v149, v147
	s_nop 1
	v_permlane32_swap_b32_e32 v147, v149
	v_mov_b32_dpp v131, v131 quad_perm:[1,0,3,2] row_mask:0xf bank_mask:0xf bound_ctrl:1
	v_fmac_f32_e32 v131, v197, v1
	s_nop 1
	v_add_f32_dpp v1, v131, v131 quad_perm:[2,3,0,1] row_mask:0xf bank_mask:0xf bound_ctrl:1
	s_nop 1
	v_add_f32_dpp v1, v1, v1 row_ror:4 row_mask:0xf bank_mask:0xf bound_ctrl:1
	s_nop 1
	v_add_f32_dpp v1, v1, v1 row_ror:8 row_mask:0xf bank_mask:0xf bound_ctrl:1
	v_mov_b32_e32 v131, v1
	s_nop 1
	v_permlane16_swap_b32_e32 v1, v131
	v_add_f32_e32 v223, v1, v131
	v_mov_b32_e32 v224, v223
	s_nop 1
	v_permlane32_swap_b32_e32 v223, v224
	s_cbranch_scc1 .LBB0_793
	s_add_i32 s2, s23, 0xffffb97c
	v_mad_u64_u32 v[226:227], s[2:3], s2, v210, v[178:179]
	global_load_dword v184, v[226:227], off
	global_load_dword v185, v[226:227], off offset:1536
	global_load_dword v222, v[226:227], off offset:3072
; __device__ __forceinline__ float sigmoidf_(float x) { return 1.f / (1.f + __expf(-x)); }
; __device__ __forceinline__ void p2_rwkv_prep(const Params& P, float* lds) {
;     ...
;                 const float r = cr + (qr - cr) * mur, kraw = ck + (qk - ck) * muk, v = cv + (qv - cv) * muv;
;                 qr = cr; qk = ck; qv = cv;
;                 const float aw = w0c + yt[tk * 64 + cc], aa = a0c + yt[(CT + tk) * 64 + cc];
;                 const float w = __expf(-DECAY_SCALE * sigmoidf_(aw)), a = sigmoidf_(aa);
;                 const float kkv = kraw * kkc;
;                 const float n2 = wave_sum_fast(kkv * kkv);
;                 const float kk = kkv * rsqrtf(fmaxf(n2, 1e-12f));
;                 const float kmod = kraw * (1.f + (a - 1.f) * kac);
;                 const float bb = kk * a;
;                 const float br = wave_sum_fast(bb * r);
;                 ekk[tk - tg] = kk; ew[tk - tg] = w; ebb[tk - tg] = bb; ekm[tk - tg] = kmod; ewr[tk - tg] = w * r - kk * br; ev[tk - tg] = v;
;                 ebr[tk - tg] = br; ekr[tk - tg] = wave_sum_fast(kmod * r); erk[tk - tg] = wave_sum_fast(r * kmod * rkc);
;             }
; #pragma unroll
;             for (int tk = tg; tk < tg + 4; ++tk) {
;                 float* blk = RSB + ((size_t)(tok0 + tk) * RH + h) * RSB_BLK;
;                 float* oq = ot + (tk & 1) * 384;
;                 oq[cc] = ekk[tk - tg]; oq[64 + cc] = ew[tk - tg]; oq[128 + cc] = ebb[tk - tg]; oq[192 + cc] = ekm[tk - tg]; oq[256 + cc] = ewr[tk - tg]; oq[320 + cc] = ev[tk - tg];
;                 __builtin_amdgcn_wave_barrier();
;                 *(float4*)(blk + 4 * lane) = *(const float4*)(oq + 4 * lane);
;                 if (lane < 32) *(float4*)(blk + 256 + 4 * lane) = *(const float4*)(oq + 256 + 4 * lane);
;                 if (lane == 0) *(float4*)(blk + 384) = make_float4(ebr[tk - tg], ekr[tk - tg], erk[tk - tg], 0.f);
.LBB0_793:
	v_add_f32_e32 v1, v190, v134
	v_mul_f32_e32 v1, 0xbfb8aa3b, v1
	v_exp_f32_e32 v1, v1
	v_sub_f32_e32 v153, v130, v213
	v_pk_add_f32 v[134:135], v[136:137], v[150:151]
	s_add_i32 s21, s23, 0xfffff980
	v_add_f32_e32 v1, 1.0, v1
	v_div_scale_f32 v130, s[2:3], v1, v1, 1.0
	v_rcp_f32_e32 v131, v130
	v_div_scale_f32 v136, vcc, 1.0, v1, 1.0
	s_waitcnt vmcnt(1)
	v_sub_f32_e32 v151, v185, v183
	v_fma_f32 v137, -v130, v131, 1.0
	v_fmac_f32_e32 v131, v137, v131
	v_mul_f32_e32 v137, v136, v131
	v_fma_f32 v150, -v130, v137, v136
	v_fmac_f32_e32 v137, v150, v131
	v_fma_f32 v130, -v130, v137, v136
	v_div_fmas_f32 v130, v130, v131, v137
	v_div_fixup_f32 v1, v130, v1, 1.0
	v_mul_f32_e32 v1, 0xbf1b4598, v1
	v_mul_f32_e32 v1, 0x3fb8aa3b, v1
	ds_read2st64_b32 v[130:131], v199 offset0:35 offset1:43
	v_exp_f32_e32 v228, v1
	v_mul_f32_e32 v1, v132, v134
	v_mad_u64_u32 v[136:137], s[2:3], s21, v208, v[176:177]
	v_fma_f32 v229, v152, v228, -v1
	s_waitcnt lgkmcnt(0)
	v_add_f32_e32 v1, v194, v131
	v_mul_f32_e32 v1, 0xbfb8aa3b, v1
	v_exp_f32_e32 v150, v1
	global_load_ushort v165, v[136:137], off
	global_load_ushort v166, v[136:137], off offset:768
	global_load_ushort v1, v[136:137], off offset:1536
	v_mov_b32_e32 v152, v183
	v_fmac_f32_e32 v152, v195, v151
	v_add_f32_e32 v136, 1.0, v150
	v_div_scale_f32 v137, s[2:3], v136, v136, 1.0
	v_rcp_f32_e32 v150, v137
	v_fmac_f32_e32 v213, v191, v153
	v_sub_f32_e32 v131, v184, v182
	v_fma_f32 v131, v196, v131, v182
	v_fma_f32 v151, -v137, v150, 1.0
	v_fmac_f32_e32 v150, v151, v150
	v_div_scale_f32 v151, vcc, 1.0, v136, 1.0
	v_mul_f32_e32 v153, v151, v150
	v_fma_f32 v184, -v137, v153, v151
	v_fmac_f32_e32 v153, v184, v150
	v_fma_f32 v137, -v137, v153, v151
	v_mul_f32_e32 v151, v193, v152
	v_mul_f32_e32 v184, v151, v151
	v_div_fmas_f32 v137, v137, v150, v153
	v_div_fixup_f32 v136, v137, v136, 1.0
	v_mov_b32_dpp v184, v184 quad_perm:[1,0,3,2] row_mask:0xf bank_mask:0xf bound_ctrl:1
	v_fmac_f32_e32 v184, v151, v151
	v_add_f32_e32 v137, -1.0, v136
	v_fma_f32 v137, v192, v137, 1.0
	v_add_f32_dpp v184, v184, v184 quad_perm:[2,3,0,1] row_mask:0xf bank_mask:0xf bound_ctrl:1
	s_mul_hi_u32 s35, s31, 6
	s_mul_i32 s31, s31, 6
	v_add_f32_dpp v184, v184, v184 row_ror:4 row_mask:0xf bank_mask:0xf bound_ctrl:1
	v_mul_f32_e32 v253, v132, v255
	v_mul_f32_e32 v254, v228, v255
	ds_write2st64_b32 v200, v253, v254 offset0:160 offset1:161
	v_mul_f32_e32 v253, v229, v255
	ds_write2st64_b32 v200, v253, v213 offset0:164 offset1:165
	v_cndmask_b32_e64 v255, v254, 1.0, s[98:99]
	v_rcp_f32_e32 v254, v255
	s_nop 0
	v_mul_f32_e32 v253, v155, v254
	v_mul_f32_e32 v254, v154, v254
	ds_write2st64_b32 v200, v253, v254 offset0:162 offset1:163
	v_add_f32_dpp v184, v184, v184 row_ror:8 row_mask:0xf bank_mask:0xf bound_ctrl:1
	v_mov_b32_e32 v185, v184
	s_nop 1
	v_permlane16_swap_b32_e32 v184, v185
	v_add_f32_e32 v184, v184, v185
	v_mov_b32_e32 v185, v184
	s_nop 1
	v_permlane32_swap_b32_e32 v184, v185
	v_add_f32_e32 v184, v184, v185
	v_max_f32_e32 v184, 0x2b8cbccc, v184
	v_rsq_f32_e32 v184, v184
	v_mul_f32_e32 v185, v152, v137
	ds_read_b128 v[228:231], v201
	v_or_b32_e32 v232, s31, v170
	v_mul_f32_e32 v184, v151, v184
	v_mul_f32_e32 v225, v136, v184
	v_mul_f32_e32 v136, v131, v225
	v_lshlrev_b32_e32 v132, 2, v172
	s_nop 0
	v_mov_b32_dpp v136, v136 quad_perm:[1,0,3,2] row_mask:0xf bank_mask:0xf bound_ctrl:1
	v_fmac_f32_e32 v136, v131, v225
	s_nop 1
	v_add_f32_dpp v136, v136, v136 quad_perm:[2,3,0,1] row_mask:0xf bank_mask:0xf bound_ctrl:1
	s_nop 1
	v_add_f32_dpp v136, v136, v136 row_ror:4 row_mask:0xf bank_mask:0xf bound_ctrl:1
	s_nop 1
	v_add_f32_dpp v136, v136, v136 row_ror:8 row_mask:0xf bank_mask:0xf bound_ctrl:1
	v_mov_b32_e32 v137, v136
	s_nop 1
	v_permlane16_swap_b32_e32 v136, v137
	v_add_f32_e32 v150, v136, v137
	v_mul_f32_e32 v136, v131, v185
	v_mov_b32_e32 v152, v150
	s_nop 1
	v_permlane32_swap_b32_e32 v150, v152
	v_mov_b32_dpp v137, v136 quad_perm:[1,0,3,2] row_mask:0xf bank_mask:0xf bound_ctrl:1
	v_fmac_f32_e32 v137, v131, v185
	s_nop 1
	v_add_f32_dpp v137, v137, v137 quad_perm:[2,3,0,1] row_mask:0xf bank_mask:0xf bound_ctrl:1
	s_nop 1
	v_add_f32_dpp v137, v137, v137 row_ror:4 row_mask:0xf bank_mask:0xf bound_ctrl:1
	s_nop 1
	v_add_f32_dpp v137, v137, v137 row_ror:8 row_mask:0xf bank_mask:0xf bound_ctrl:1
	v_mov_b32_e32 v151, v137
	s_nop 1
	v_permlane16_swap_b32_e32 v137, v151
	v_add_f32_e32 v151, v137, v151
	v_mul_f32_e32 v137, v197, v136
	v_mov_b32_e32 v153, v151
	s_nop 1
	v_permlane32_swap_b32_e32 v151, v153
	v_mov_b32_dpp v137, v137 quad_perm:[1,0,3,2] row_mask:0xf bank_mask:0xf bound_ctrl:1
	v_fmac_f32_e32 v137, v197, v136
	s_nop 1
	v_add_f32_dpp v136, v137, v137 quad_perm:[2,3,0,1] row_mask:0xf bank_mask:0xf bound_ctrl:1
	s_nop 1
	v_add_f32_dpp v136, v136, v136 row_ror:4 row_mask:0xf bank_mask:0xf bound_ctrl:1
	s_nop 1
	v_add_f32_dpp v136, v136, v136 row_ror:8 row_mask:0xf bank_mask:0xf bound_ctrl:1
	v_mov_b32_e32 v137, v136
	s_nop 1
	v_permlane16_swap_b32_e32 v136, v137
	v_add_f32_e32 v226, v136, v137
	v_mov_b64_e32 v[136:137], s[18:19]
	v_mad_u64_u32 v[154:155], s[2:3], v232, s25, v[136:137]
	v_mov_b32_e32 v227, v226
	v_mad_u32_u24 v155, s35, v211, v155
	s_nop 0
	v_permlane32_swap_b32_e32 v226, v227
	v_lshl_add_u64 v[136:137], v[154:155], 0, v[132:133]
	s_waitcnt lgkmcnt(0)
	global_store_dwordx4 v[136:137], v[228:231], off
	s_and_saveexec_b64 s[2:3], s[10:11]
	s_cbranch_execz .LBB0_795
	ds_read_b128 v[228:231], v202
	s_waitcnt lgkmcnt(0)
	global_store_dwordx4 v[136:137], v[228:231], off offset:1024

; __device__ __forceinline__ float sigmoidf_(float x) { return 1.f / (1.f + __expf(-x)); }
; __device__ __forceinline__ void p2_rwkv_prep(const Params& P, float* lds) {
;     ...
;                 const float aw = w0c + yt[tk * 64 + cc], aa = a0c + yt[(CT + tk) * 64 + cc];
;                 const float w = __expf(-DECAY_SCALE * sigmoidf_(aw)), a = sigmoidf_(aa);
;                 const float kkv = kraw * kkc;
;                 const float n2 = wave_sum_fast(kkv * kkv);
;                 const float kk = kkv * rsqrtf(fmaxf(n2, 1e-12f));
;                 const float kmod = kraw * (1.f + (a - 1.f) * kac);
;                 const float bb = kk * a;
;                 const float br = wave_sum_fast(bb * r);
;                 ekk[tk - tg] = kk; ew[tk - tg] = w; ebb[tk - tg] = bb; ekm[tk - tg] = kmod; ewr[tk - tg] = w * r - kk * br; ev[tk - tg] = v;
;                 ebr[tk - tg] = br; ekr[tk - tg] = wave_sum_fast(kmod * r); erk[tk - tg] = wave_sum_fast(r * kmod * rkc);
;             }
; #pragma unroll
;             for (int tk = tg; tk < tg + 4; ++tk) {
;                 float* blk = RSB + ((size_t)(tok0 + tk) * RH + h) * RSB_BLK;
;                 float* oq = ot + (tk & 1) * 384;
;                 oq[cc] = ekk[tk - tg]; oq[64 + cc] = ew[tk - tg]; oq[128 + cc] = ebb[tk - tg]; oq[192 + cc] = ekm[tk - tg]; oq[256 + cc] = ewr[tk - tg]; oq[320 + cc] = ev[tk - tg];
;                 __builtin_amdgcn_wave_barrier();
;                 *(float4*)(blk + 4 * lane) = *(const float4*)(oq + 4 * lane);
;                 if (lane < 32) *(float4*)(blk + 256 + 4 * lane) = *(const float4*)(oq + 256 + 4 * lane);
;                 if (lane == 0) *(float4*)(blk + 384) = make_float4(ebr[tk - tg], ekr[tk - tg], erk[tk - tg], 0.f);
.LBB0_797:
	s_or_b64 exec, exec, s[2:3]
	s_nop 0
	v_add_f32_e32 v134, v190, v138
	v_mul_f32_e32 v134, 0xbfb8aa3b, v134
	v_exp_f32_e32 v134, v134
	v_sub_f32_e32 v136, v167, v214
	v_fmac_f32_e32 v214, v191, v136
	v_add_f32_e32 v137, 1.0, v134
	v_div_scale_f32 v138, s[2:3], v137, v137, 1.0
	v_rcp_f32_e32 v154, v138
	v_pk_add_f32 v[134:135], v[142:143], v[144:145]
	v_div_scale_f32 v142, vcc, 1.0, v137, 1.0
	v_fma_f32 v143, -v138, v154, 1.0
	v_fmac_f32_e32 v154, v143, v154
	v_mul_f32_e32 v143, v142, v154
	v_fma_f32 v144, -v138, v143, v142
	v_fmac_f32_e32 v143, v144, v154
	v_fma_f32 v138, -v138, v143, v142
	v_div_fmas_f32 v138, v138, v154, v143
	v_div_fixup_f32 v137, v138, v137, 1.0
	v_mul_f32_e32 v137, 0xbf1b4598, v137
	v_mul_f32_e32 v137, 0x3fb8aa3b, v137
	v_exp_f32_e32 v142, v137
	v_mul_f32_e32 v136, v188, v134
	s_add_i32 s2, s23, 0xfffff97a
	v_fma_f32 v143, v139, v142, -v136
	v_mul_f32_e32 v253, v188, v255
	v_mul_f32_e32 v254, v142, v255
	ds_write2st64_b32 v203, v253, v254 offset0:166 offset1:167
	v_mul_f32_e32 v253, v143, v255
	ds_write2st64_b32 v203, v253, v214 offset0:170 offset1:171
	v_cndmask_b32_e64 v255, v254, 1.0, s[98:99]
	v_rcp_f32_e32 v254, v255
	s_nop 0
	v_mul_f32_e32 v253, v217, v254
	v_mul_f32_e32 v254, v189, v254
	ds_write2st64_b32 v203, v253, v254 offset0:168 offset1:169
	ds_read_b128 v[142:145], v204
	v_mad_u64_u32 v[136:137], s[2:3], s2, 6, v[170:171]
	v_mov_b64_e32 v[138:139], s[18:19]
	v_mad_u64_u32 v[138:139], s[2:3], v136, s25, v[138:139]
	v_mad_u32_u24 v139, v137, s25, v139
	v_lshl_add_u64 v[136:137], v[138:139], 0, v[132:133]
	s_waitcnt lgkmcnt(0)
	global_store_dwordx4 v[136:137], v[142:145], off
	s_and_saveexec_b64 s[2:3], s[10:11]
	s_cbranch_execz .LBB0_799
	ds_read_b128 v[142:145], v205
	s_waitcnt lgkmcnt(0)
	global_store_dwordx4 v[136:137], v[142:145], off offset:1024

; __device__ __forceinline__ float bf2f(bf16_t b) { return __uint_as_float(((unsigned)b) << 16); }
; __device__ __forceinline__ float sigmoidf_(float x) { return 1.f / (1.f + __expf(-x)); }
; __device__ __forceinline__ void p2_rwkv_prep(const Params& P, float* lds) {
;     ...
;             for (int tk = tg; tk < tg + 4; ++tk) {
;                 const int tok = tok0 + tk;
;                 if (tok >= NTOK) { const float* p = P.state_shift + (size_t)(tok - NTOK) * RCOLS + tid; qr = p[0]; qk = p[RW]; qv = p[2 * RW]; }
;                 const float cr = nr[tk & 3], ck = nk[tk & 3], cv = nv[tk & 3];
;                 if (tk + 4 < CT) { const bf16_t* p = prw + (size_t)(tok + 4) * RCOLS + tid; nr[tk & 3] = bf2f(p[0]); nk[tk & 3] = bf2f(p[RW]); nv[tk & 3] = bf2f(p[2 * RW]); }
;                 const float r = cr + (qr - cr) * mur, kraw = ck + (qk - ck) * muk, v = cv + (qv - cv) * muv;
;                 qr = cr; qk = ck; qv = cv;
;                 const float aw = w0c + yt[tk * 64 + cc], aa = a0c + yt[(CT + tk) * 64 + cc];
;                 const float w = __expf(-DECAY_SCALE * sigmoidf_(aw)), a = sigmoidf_(aa);
;                 const float kkv = kraw * kkc;
;                 const float n2 = wave_sum_fast(kkv * kkv);
;                 const float kk = kkv * rsqrtf(fmaxf(n2, 1e-12f));
;                 const float kmod = kraw * (1.f + (a - 1.f) * kac);
;                 const float bb = kk * a;
;                 const float br = wave_sum_fast(bb * r);
;                 ekk[tk - tg] = kk; ew[tk - tg] = w; ebb[tk - tg] = bb; ekm[tk - tg] = kmod; ewr[tk - tg] = w * r - kk * br; ev[tk - tg] = v;
;                 ebr[tk - tg] = br; ekr[tk - tg] = wave_sum_fast(kmod * r); erk[tk - tg] = wave_sum_fast(r * kmod * rkc);
.LBB0_809:
	s_or_b64 exec, exec, s[2:3]
	s_cmpk_lt_i32 s16, 0x4000
	s_cbranch_scc1 .LBB0_811
	s_add_i32 s2, s23, 0xffffb97d
	v_mad_u64_u32 v[130:131], s[2:3], s2, v210, v[178:179]
	global_load_dword v182, v[130:131], off
	global_load_dword v183, v[130:131], off offset:1536
	global_load_dword v215, v[130:131], off offset:3072
.LBB0_811:
	ds_read2st64_b32 v[134:135], v199 offset0:36 offset1:44
	v_lshlrev_b32_e32 v188, 16, v156
	s_waitcnt vmcnt(2)
	v_sub_f32_e32 v131, v182, v188
	v_fma_f32 v152, v196, v131, v188
	v_lshlrev_b32_e32 v189, 16, v158
	s_waitcnt lgkmcnt(0)
	v_add_f32_e32 v130, v194, v135
	v_mul_f32_e32 v130, 0xbfb8aa3b, v130
	v_exp_f32_e32 v130, v130
	s_waitcnt vmcnt(1)
	v_sub_f32_e32 v135, v183, v189
	v_fma_f32 v135, v195, v135, v189
	v_lshlrev_b32_e32 v213, 16, v157
	v_add_f32_e32 v130, 1.0, v130
	v_div_scale_f32 v131, s[2:3], v130, v130, 1.0
	v_rcp_f32_e32 v136, v131
	v_div_scale_f32 v137, vcc, 1.0, v130, 1.0
	s_cmpk_lt_i32 s17, 0x4000
	v_fma_f32 v138, -v131, v136, 1.0
	v_fmac_f32_e32 v136, v138, v136
	v_mul_f32_e32 v138, v137, v136
	v_fma_f32 v139, -v131, v138, v137
	v_fmac_f32_e32 v138, v139, v136
	v_fma_f32 v131, -v131, v138, v137
	v_mul_f32_e32 v137, v193, v135
	v_mul_f32_e32 v139, v137, v137
	v_div_fmas_f32 v131, v131, v136, v138
	v_div_fixup_f32 v130, v131, v130, 1.0
	v_mov_b32_dpp v139, v139 quad_perm:[1,0,3,2] row_mask:0xf bank_mask:0xf bound_ctrl:1
	v_fmac_f32_e32 v139, v137, v137
	v_add_f32_e32 v131, -1.0, v130
	v_fma_f32 v131, v192, v131, 1.0
	v_add_f32_dpp v139, v139, v139 quad_perm:[2,3,0,1] row_mask:0xf bank_mask:0xf bound_ctrl:1
	v_mul_f32_e32 v155, v135, v131
	v_mov_b32_e32 v157, v213
	v_add_f32_dpp v139, v139, v139 row_ror:4 row_mask:0xf bank_mask:0xf bound_ctrl:1
	v_mov_b32_e32 v138, v188
	s_nop 0
	v_add_f32_dpp v139, v139, v139 row_ror:8 row_mask:0xf bank_mask:0xf bound_ctrl:1
	v_mov_b32_e32 v140, v139
	s_nop 1
	v_permlane16_swap_b32_e32 v139, v140
	v_add_f32_e32 v139, v139, v140
	v_mov_b32_e32 v140, v139
	s_nop 1
	v_permlane32_swap_b32_e32 v139, v140
	v_add_f32_e32 v139, v139, v140
	v_max_f32_e32 v139, 0x2b8cbccc, v139
	v_rsq_f32_e32 v139, v139
	s_nop 0
	v_mul_f32_e32 v154, v137, v139
	v_mul_f32_e32 v156, v130, v154
	v_mul_f32_e32 v130, v152, v156
	s_nop 1
	v_mov_b32_dpp v130, v130 quad_perm:[1,0,3,2] row_mask:0xf bank_mask:0xf bound_ctrl:1
	v_fmac_f32_e32 v130, v152, v156
	s_nop 1
	v_add_f32_dpp v130, v130, v130 quad_perm:[2,3,0,1] row_mask:0xf bank_mask:0xf bound_ctrl:1
	s_nop 1
	v_add_f32_dpp v130, v130, v130 row_ror:4 row_mask:0xf bank_mask:0xf bound_ctrl:1
	s_nop 1
	v_add_f32_dpp v130, v130, v130 row_ror:8 row_mask:0xf bank_mask:0xf bound_ctrl:1
	v_mov_b32_e32 v131, v130
	s_nop 1
	v_permlane16_swap_b32_e32 v130, v131
	v_add_f32_e32 v136, v130, v131
	v_mul_f32_e32 v130, v152, v155
	v_mov_b32_e32 v148, v136
	s_nop 1
	v_permlane32_swap_b32_e32 v136, v148
	v_mov_b32_dpp v131, v130 quad_perm:[1,0,3,2] row_mask:0xf bank_mask:0xf bound_ctrl:1
	v_fmac_f32_e32 v131, v152, v155
	s_nop 1
	v_add_f32_dpp v131, v131, v131 quad_perm:[2,3,0,1] row_mask:0xf bank_mask:0xf bound_ctrl:1
	s_nop 1
	v_add_f32_dpp v131, v131, v131 row_ror:4 row_mask:0xf bank_mask:0xf bound_ctrl:1
	s_nop 1
	v_add_f32_dpp v131, v131, v131 row_ror:8 row_mask:0xf bank_mask:0xf bound_ctrl:1
	v_mov_b32_e32 v135, v131
	s_nop 1
	v_permlane16_swap_b32_e32 v131, v135
	v_add_f32_e32 v137, v131, v135
	v_mul_f32_e32 v131, v197, v130
	v_mov_b32_e32 v149, v137
	s_nop 1
	v_permlane32_swap_b32_e32 v137, v149
	v_mov_b32_dpp v131, v131 quad_perm:[1,0,3,2] row_mask:0xf bank_mask:0xf bound_ctrl:1
	v_fmac_f32_e32 v131, v197, v130
	v_mov_b32_e32 v135, v189
	s_nop 0
	v_add_f32_dpp v130, v131, v131 quad_perm:[2,3,0,1] row_mask:0xf bank_mask:0xf bound_ctrl:1
	s_nop 1
	v_add_f32_dpp v130, v130, v130 row_ror:4 row_mask:0xf bank_mask:0xf bound_ctrl:1
	s_nop 1
	v_add_f32_dpp v130, v130, v130 row_ror:8 row_mask:0xf bank_mask:0xf bound_ctrl:1
	v_mov_b32_e32 v131, v130
	s_nop 1
	v_permlane16_swap_b32_e32 v130, v131
	v_add_f32_e32 v158, v130, v131
	v_mov_b32_e32 v167, v158
	s_nop 1
	v_permlane32_swap_b32_e32 v158, v167
	s_cbranch_scc1 .LBB0_813
	s_add_i32 s2, s23, 0xffffb97e
	v_mad_u64_u32 v[130:131], s[2:3], s2, v210, v[178:179]
	global_load_dword v138, v[130:131], off
	global_load_dword v135, v[130:131], off offset:1536
	global_load_dword v157, v[130:131], off offset:3072
; __device__ __forceinline__ float bf2f(bf16_t b) { return __uint_as_float(((unsigned)b) << 16); }
; __device__ __forceinline__ float sigmoidf_(float x) { return 1.f / (1.f + __expf(-x)); }
; __device__ __forceinline__ void p2_rwkv_prep(const Params& P, float* lds) {
;     ...
;             for (int tk = tg; tk < tg + 4; ++tk) {
;                 const int tok = tok0 + tk;
;                 if (tok >= NTOK) { const float* p = P.state_shift + (size_t)(tok - NTOK) * RCOLS + tid; qr = p[0]; qk = p[RW]; qv = p[2 * RW]; }
;                 const float cr = nr[tk & 3], ck = nk[tk & 3], cv = nv[tk & 3];
;                 if (tk + 4 < CT) { const bf16_t* p = prw + (size_t)(tok + 4) * RCOLS + tid; nr[tk & 3] = bf2f(p[0]); nk[tk & 3] = bf2f(p[RW]); nv[tk & 3] = bf2f(p[2 * RW]); }
;                 const float r = cr + (qr - cr) * mur, kraw = ck + (qk - ck) * muk, v = cv + (qv - cv) * muv;
;                 qr = cr; qk = ck; qv = cv;
;                 const float aw = w0c + yt[tk * 64 + cc], aa = a0c + yt[(CT + tk) * 64 + cc];
;                 const float w = __expf(-DECAY_SCALE * sigmoidf_(aw)), a = sigmoidf_(aa);
;                 const float kkv = kraw * kkc;
;                 const float n2 = wave_sum_fast(kkv * kkv);
;                 const float kk = kkv * rsqrtf(fmaxf(n2, 1e-12f));
;                 const float kmod = kraw * (1.f + (a - 1.f) * kac);
;                 const float bb = kk * a;
;                 const float br = wave_sum_fast(bb * r);
;                 ekk[tk - tg] = kk; ew[tk - tg] = w; ebb[tk - tg] = bb; ekm[tk - tg] = kmod; ewr[tk - tg] = w * r - kk * br; ev[tk - tg] = v;
;                 ebr[tk - tg] = br; ekr[tk - tg] = wave_sum_fast(kmod * r); erk[tk - tg] = wave_sum_fast(r * kmod * rkc);
.LBB0_813:
	ds_read2st64_b32 v[130:131], v199 offset0:37 offset1:45
	v_lshlrev_b32_e32 v186, 16, v159
	v_lshlrev_b32_e32 v187, 16, v161
	s_waitcnt vmcnt(1)
	v_sub_f32_e32 v135, v135, v187
	v_fma_f32 v135, v195, v135, v187
	s_waitcnt lgkmcnt(0)
	v_add_f32_e32 v131, v194, v131
	v_mul_f32_e32 v131, 0xbfb8aa3b, v131
	v_exp_f32_e32 v139, v131
	v_sub_f32_e32 v131, v138, v186
	v_fma_f32 v131, v196, v131, v186
	v_lshlrev_b32_e32 v214, 16, v160
	v_add_f32_e32 v138, 1.0, v139
	v_div_scale_f32 v139, s[2:3], v138, v138, 1.0
	v_rcp_f32_e32 v140, v139
	v_div_scale_f32 v141, vcc, 1.0, v138, 1.0
	s_cmpk_lt_i32 s20, 0x4000
	v_fma_f32 v142, -v139, v140, 1.0
	v_fmac_f32_e32 v140, v142, v140
	v_mul_f32_e32 v142, v141, v140
	v_fma_f32 v143, -v139, v142, v141
	v_fmac_f32_e32 v142, v143, v140
	v_fma_f32 v139, -v139, v142, v141
	v_mul_f32_e32 v141, v193, v135
	v_mul_f32_e32 v143, v141, v141
	v_div_fmas_f32 v139, v139, v140, v142
	v_div_fixup_f32 v138, v139, v138, 1.0
	v_mov_b32_dpp v143, v143 quad_perm:[1,0,3,2] row_mask:0xf bank_mask:0xf bound_ctrl:1
	v_fmac_f32_e32 v143, v141, v141
	v_add_f32_e32 v139, -1.0, v138
	v_fma_f32 v139, v192, v139, 1.0
	v_add_f32_dpp v143, v143, v143 quad_perm:[2,3,0,1] row_mask:0xf bank_mask:0xf bound_ctrl:1
	v_mul_f32_e32 v160, v135, v139
	v_mov_b32_e32 v168, v214
	v_add_f32_dpp v143, v143, v143 row_ror:4 row_mask:0xf bank_mask:0xf bound_ctrl:1
	s_nop 1
	v_add_f32_dpp v143, v143, v143 row_ror:8 row_mask:0xf bank_mask:0xf bound_ctrl:1
	v_mov_b32_e32 v144, v143
	s_nop 1
	v_permlane16_swap_b32_e32 v143, v144
	v_add_f32_e32 v143, v143, v144
	v_mov_b32_e32 v144, v143
	s_nop 1
	v_permlane32_swap_b32_e32 v143, v144
	v_add_f32_e32 v143, v143, v144
	v_max_f32_e32 v143, 0x2b8cbccc, v143
	v_rsq_f32_e32 v143, v143
	v_mov_b32_e32 v144, v186
	v_mul_f32_e32 v159, v141, v143
	v_mul_f32_e32 v161, v138, v159
	v_mul_f32_e32 v135, v131, v161
	s_nop 1
	v_mov_b32_dpp v135, v135 quad_perm:[1,0,3,2] row_mask:0xf bank_mask:0xf bound_ctrl:1
	v_fmac_f32_e32 v135, v131, v161
	s_nop 1
	v_add_f32_dpp v135, v135, v135 quad_perm:[2,3,0,1] row_mask:0xf bank_mask:0xf bound_ctrl:1
	s_nop 1
	v_add_f32_dpp v135, v135, v135 row_ror:4 row_mask:0xf bank_mask:0xf bound_ctrl:1
	s_nop 1
	v_add_f32_dpp v135, v135, v135 row_ror:8 row_mask:0xf bank_mask:0xf bound_ctrl:1
	v_mov_b32_e32 v138, v135
	s_nop 1
	v_permlane16_swap_b32_e32 v135, v138
	v_add_f32_e32 v138, v135, v138
	v_mul_f32_e32 v135, v131, v160
	v_mul_f32_e32 v142, v197, v135
	v_mov_b32_e32 v140, v138
	v_mov_b32_dpp v139, v135 quad_perm:[1,0,3,2] row_mask:0xf bank_mask:0xf bound_ctrl:1
	v_mov_b32_dpp v142, v142 quad_perm:[1,0,3,2] row_mask:0xf bank_mask:0xf bound_ctrl:1
	v_fmac_f32_e32 v139, v131, v160
	v_fmac_f32_e32 v142, v197, v135
	v_permlane32_swap_b32_e32 v138, v140
	v_add_f32_dpp v139, v139, v139 quad_perm:[2,3,0,1] row_mask:0xf bank_mask:0xf bound_ctrl:1
	v_add_f32_dpp v135, v142, v142 quad_perm:[2,3,0,1] row_mask:0xf bank_mask:0xf bound_ctrl:1
	s_nop 0
	v_add_f32_dpp v139, v139, v139 row_ror:4 row_mask:0xf bank_mask:0xf bound_ctrl:1
	v_add_f32_dpp v135, v135, v135 row_ror:4 row_mask:0xf bank_mask:0xf bound_ctrl:1
	s_nop 0
	v_add_f32_dpp v139, v139, v139 row_ror:8 row_mask:0xf bank_mask:0xf bound_ctrl:1
	v_add_f32_dpp v135, v135, v135 row_ror:8 row_mask:0xf bank_mask:0xf bound_ctrl:1
	v_mov_b32_e32 v141, v139
	v_mov_b32_e32 v142, v135
	s_nop 0
	v_permlane16_swap_b32_e32 v139, v141
	v_permlane16_swap_b32_e32 v135, v142
	v_add_f32_e32 v139, v139, v141
	v_add_f32_e32 v169, v135, v142
	v_mov_b32_e32 v141, v139
	v_mov_b32_e32 v217, v169
	s_nop 0
	v_permlane32_swap_b32_e32 v139, v141
	v_permlane32_swap_b32_e32 v169, v217
	v_mov_b32_e32 v135, v187
	s_cbranch_scc1 .LBB0_815
	s_add_i32 s2, s23, 0xffffb97f
	v_mad_u64_u32 v[142:143], s[2:3], s2, v210, v[178:179]
	global_load_dword v144, v[142:143], off
	global_load_dword v135, v[142:143], off offset:1536
	global_load_dword v168, v[142:143], off offset:3072
; __device__ __forceinline__ float bf2f(bf16_t b) { return __uint_as_float(((unsigned)b) << 16); }
; __device__ __forceinline__ float sigmoidf_(float x) { return 1.f / (1.f + __expf(-x)); }
; __device__ __forceinline__ void p2_rwkv_prep(const Params& P, float* lds) {
;     ...
;             for (int tk = tg; tk < tg + 4; ++tk) {
;                 const int tok = tok0 + tk;
;                 if (tok >= NTOK) { const float* p = P.state_shift + (size_t)(tok - NTOK) * RCOLS + tid; qr = p[0]; qk = p[RW]; qv = p[2 * RW]; }
;                 const float cr = nr[tk & 3], ck = nk[tk & 3], cv = nv[tk & 3];
;                 if (tk + 4 < CT) { const bf16_t* p = prw + (size_t)(tok + 4) * RCOLS + tid; nr[tk & 3] = bf2f(p[0]); nk[tk & 3] = bf2f(p[RW]); nv[tk & 3] = bf2f(p[2 * RW]); }
;                 const float r = cr + (qr - cr) * mur, kraw = ck + (qk - ck) * muk, v = cv + (qv - cv) * muv;
;                 qr = cr; qk = ck; qv = cv;
;                 const float aw = w0c + yt[tk * 64 + cc], aa = a0c + yt[(CT + tk) * 64 + cc];
;                 const float w = __expf(-DECAY_SCALE * sigmoidf_(aw)), a = sigmoidf_(aa);
;                 const float kkv = kraw * kkc;
;                 const float n2 = wave_sum_fast(kkv * kkv);
;                 const float kk = kkv * rsqrtf(fmaxf(n2, 1e-12f));
;                 const float kmod = kraw * (1.f + (a - 1.f) * kac);
;                 const float bb = kk * a;
;                 const float br = wave_sum_fast(bb * r);
;                 ekk[tk - tg] = kk; ew[tk - tg] = w; ebb[tk - tg] = bb; ekm[tk - tg] = kmod; ewr[tk - tg] = w * r - kk * br; ev[tk - tg] = v;
;                 ebr[tk - tg] = br; ekr[tk - tg] = wave_sum_fast(kmod * r); erk[tk - tg] = wave_sum_fast(r * kmod * rkc);
.LBB0_815:
	ds_read2st64_b32 v[142:143], v199 offset0:38 offset1:46
	v_lshlrev_b32_e32 v184, 16, v162
	v_lshlrev_b32_e32 v185, 16, v164
	s_waitcnt vmcnt(1)
	v_sub_f32_e32 v135, v135, v185
	v_fma_f32 v135, v195, v135, v185
	s_waitcnt lgkmcnt(0)
	v_add_f32_e32 v143, v194, v143
	v_mul_f32_e32 v143, 0xbfb8aa3b, v143
	v_exp_f32_e32 v145, v143
	v_sub_f32_e32 v143, v144, v184
	v_lshlrev_b32_e32 v216, 16, v163
	v_fma_f32 v143, v196, v143, v184
	v_add_f32_e32 v144, 1.0, v145
	v_div_scale_f32 v145, s[2:3], v144, v144, 1.0
	v_rcp_f32_e32 v146, v145
	v_div_scale_f32 v147, vcc, 1.0, v144, 1.0
	s_cmpk_lt_i32 s21, 0x4000
	v_fma_f32 v150, -v145, v146, 1.0
	v_fmac_f32_e32 v146, v150, v146
	v_mul_f32_e32 v150, v147, v146
	v_fma_f32 v151, -v145, v150, v147
	v_fmac_f32_e32 v150, v151, v146
	v_fma_f32 v145, -v145, v150, v147
	v_mul_f32_e32 v147, v193, v135
	v_mul_f32_e32 v151, v147, v147
	v_div_fmas_f32 v145, v145, v146, v150
	v_div_fixup_f32 v144, v145, v144, 1.0
	v_mov_b32_dpp v151, v151 quad_perm:[1,0,3,2] row_mask:0xf bank_mask:0xf bound_ctrl:1
	v_fmac_f32_e32 v151, v147, v147
	v_add_f32_e32 v145, -1.0, v144
	v_fma_f32 v145, v192, v145, 1.0
	v_add_f32_dpp v151, v151, v151 quad_perm:[2,3,0,1] row_mask:0xf bank_mask:0xf bound_ctrl:1
	v_mul_f32_e32 v164, v135, v145
	v_mov_b32_e32 v162, v216
	v_add_f32_dpp v151, v151, v151 row_ror:4 row_mask:0xf bank_mask:0xf bound_ctrl:1
	v_mov_b32_e32 v221, v184
	s_nop 0
	v_add_f32_dpp v151, v151, v151 row_ror:8 row_mask:0xf bank_mask:0xf bound_ctrl:1
	v_mov_b32_e32 v153, v151
	s_nop 1
	v_permlane16_swap_b32_e32 v151, v153
	v_add_f32_e32 v151, v151, v153
	v_mov_b32_e32 v153, v151
	s_nop 1
	v_permlane32_swap_b32_e32 v151, v153
	v_add_f32_e32 v151, v151, v153
	v_max_f32_e32 v151, 0x2b8cbccc, v151
	v_rsq_f32_e32 v151, v151
	v_mov_b32_e32 v153, v185
	v_mul_f32_e32 v163, v147, v151
	v_mul_f32_e32 v218, v144, v163
	v_mul_f32_e32 v135, v143, v218
	s_nop 1
	v_mov_b32_dpp v135, v135 quad_perm:[1,0,3,2] row_mask:0xf bank_mask:0xf bound_ctrl:1
	v_fmac_f32_e32 v135, v143, v218
	s_nop 1
	v_add_f32_dpp v135, v135, v135 quad_perm:[2,3,0,1] row_mask:0xf bank_mask:0xf bound_ctrl:1
	s_nop 1
	v_add_f32_dpp v135, v135, v135 row_ror:4 row_mask:0xf bank_mask:0xf bound_ctrl:1
	s_nop 1
	v_add_f32_dpp v135, v135, v135 row_ror:8 row_mask:0xf bank_mask:0xf bound_ctrl:1
	v_mov_b32_e32 v144, v135
	s_nop 1
	v_permlane16_swap_b32_e32 v135, v144
	v_add_f32_e32 v144, v135, v144
	v_mul_f32_e32 v135, v143, v164
	v_mul_f32_e32 v150, v197, v135
	v_mov_b32_e32 v146, v144
	v_mov_b32_dpp v145, v135 quad_perm:[1,0,3,2] row_mask:0xf bank_mask:0xf bound_ctrl:1
	v_mov_b32_dpp v150, v150 quad_perm:[1,0,3,2] row_mask:0xf bank_mask:0xf bound_ctrl:1
	v_fmac_f32_e32 v145, v143, v164
	v_fmac_f32_e32 v150, v197, v135
	v_permlane32_swap_b32_e32 v144, v146
	v_add_f32_dpp v145, v145, v145 quad_perm:[2,3,0,1] row_mask:0xf bank_mask:0xf bound_ctrl:1
	v_add_f32_dpp v135, v150, v150 quad_perm:[2,3,0,1] row_mask:0xf bank_mask:0xf bound_ctrl:1
	s_nop 0
	v_add_f32_dpp v145, v145, v145 row_ror:4 row_mask:0xf bank_mask:0xf bound_ctrl:1
	v_add_f32_dpp v135, v135, v135 row_ror:4 row_mask:0xf bank_mask:0xf bound_ctrl:1
	s_nop 0
	v_add_f32_dpp v145, v145, v145 row_ror:8 row_mask:0xf bank_mask:0xf bound_ctrl:1
	v_add_f32_dpp v135, v135, v135 row_ror:8 row_mask:0xf bank_mask:0xf bound_ctrl:1
	v_mov_b32_e32 v147, v145
	v_mov_b32_e32 v150, v135
	s_nop 0
	v_permlane16_swap_b32_e32 v145, v147
	v_permlane16_swap_b32_e32 v135, v150
	v_add_f32_e32 v145, v145, v147
	v_add_f32_e32 v219, v135, v150
	v_mov_b32_e32 v147, v145
	v_mov_b32_e32 v220, v219
	s_nop 0
	v_permlane32_swap_b32_e32 v145, v147
	v_permlane32_swap_b32_e32 v219, v220
	s_cbranch_scc1 .LBB0_817
	s_add_i32 s2, s23, 0xffffb980
	v_mad_u64_u32 v[150:151], s[2:3], s2, v210, v[178:179]
	global_load_dword v221, v[150:151], off
	global_load_dword v153, v[150:151], off offset:1536
	global_load_dword v162, v[150:151], off offset:3072

; __device__ __forceinline__ float bf2f(bf16_t b) { return __uint_as_float(((unsigned)b) << 16); }
; __device__ __forceinline__ void prep_produce(const Params& P, const bf16_t* __restrict__ prw, int ch, float* buf, int j, float mux) {
;     constexpr int CT = 8;
;     const int tok0 = ch * CT;
;     float pv = 0.f;
;     if (tok0 < NTOK && (tok0 & (SEQ - 1))) pv = bf2f(prw[(size_t)(tok0 - 1) * RCOLS + 1152 + j]);
; __device__ __forceinline__ void p2_rwkv_prep(const Params& P, float* lds) {
;     ...
;         if (tid >= RW) { if (ch + NPREP < NCHK) prep_produce(P, prw, ch + NPREP, bufn, tid - RW, mux); }
.LBB0_834:
	s_andn2_saveexec_b64 s[0:1], s[0:1]
	s_cbranch_execz .LBB0_763
	s_cmpk_gt_i32 s30, 0x733
	s_cbranch_scc1 .LBB0_763
	s_add_i32 s16, s30, 0xd0
	s_cmpk_gt_i32 s30, 0x72f
	s_cselect_b64 s[2:3], -1, 0
	s_and_b32 s16, s16, 0x1ff
	s_cmp_eq_u32 s16, 0
	s_cselect_b64 s[16:17], -1, 0
	s_or_b64 s[16:17], s[2:3], s[16:17]
	v_mov_b32_e32 v130, 0
	s_and_b64 vcc, exec, s[16:17]
	s_cbranch_vccnz .LBB0_838
	s_add_i32 s16, s23, -8
	v_mad_i64_i32 v[130:131], s[16:17], s16, v208, v[180:181]
	global_load_ushort v1, v[130:131], off offset:2304
	s_waitcnt vmcnt(0)
	v_lshlrev_b32_e32 v130, 16, v1

; #define LAS __attribute__((address_space(3)))
; __device__ __forceinline__ void p3_scan_and_sb(const Params& P, float* lds) {
;     ...
;     } else {
;         const int grp = wave >> 2, gw = wave & 3;
;         volatile LAS unsigned* gctl = (volatile LAS unsigned*)((LAS unsigned char*)lds + LDS_CTL + 32);
;         if (tid < 8) gctl[tid] = 0u;
;         __syncthreads();
;         sba::Grp4 G; G.ctr = gctl + grp; G.gen = 0u;
;         if (grp == 1) sb_decode_wave_loop(P, lds);
.LBB0_939:
	s_cmp_lt_i32 s60, 4
	s_cselect_b64 s[0:1], -1, 0
	s_cmp_gt_i32 s61, 3
	s_cselect_b64 s[2:3], -1, 0
	s_and_b64 s[34:35], s[0:1], s[2:3]
	s_andn2_b64 vcc, exec, s[34:35]
	s_cbranch_vccnz .LBB0_1576
	v_writelane_b32 v252, s34, 54
	s_cmpk_lt_u32 s56, 0x60
	v_and_b32_e32 v1, 63, v0
	v_writelane_b32 v252, s35, 55
	v_writelane_b32 v252, s80, 56
	s_cselect_b64 s[52:53], -1, 0
	s_cmpk_gt_u32 s56, 0x5f
	v_writelane_b32 v252, s81, 57
	v_writelane_b32 v252, s56, 53
	v_writelane_b32 v252, s60, 51
	s_mov_b64 s[0:1], -1
	s_waitcnt vmcnt(0)
	v_writelane_b32 v252, s61, 52
	s_barrier
	v_writelane_b32 v252, s57, 50
	s_cbranch_scc0 .LBB0_1203
	v_writelane_b32 v252, s52, 58
	v_cmp_gt_u32_e32 vcc, 8, v0
	s_nop 0
	v_writelane_b32 v252, s53, 59
	s_and_saveexec_b64 s[0:1], vcc
	v_lshl_add_u32 v2, v0, 2, 0
	v_add_u32_e32 v2, 0x26020, v2
	v_mov_b32_e32 v3, 0
	ds_write_b32 v2, v3
	s_or_b64 exec, exec, s[0:1]
	v_lshrrev_b32_e32 v94, 8, v0
	s_waitcnt lgkmcnt(0)
	s_barrier
	v_cmp_eq_u32_e32 vcc, 1, v94
	s_mov_b64 s[0:1], exec
	v_writelane_b32 v252, s0, 60
	s_nop 1
	v_writelane_b32 v252, s1, 61
	s_cmpk_gt_u32 s56, 0xcf
	s_cselect_b64 s[2:3], exec, 0
	s_or_b64 vcc, vcc, s[2:3]
	s_and_b64 s[0:1], s[0:1], vcc
	s_mov_b64 exec, s[0:1]
	s_cbranch_execz .LBB0_1092
	v_readfirstlane_b32 s2, v94
	s_cmp_eq_u32 s2, 0
	s_cselect_b32 s100, 1, 0x7fffffff
	s_add_u32 s0, s78, 0x3900
	s_addc_u32 s1, s79, 0
	v_writelane_b32 v252, s0, 62
	v_mov_b32_e32 v95, 0
	v_cmp_eq_u32_e64 s[4:5], 0, v1
	v_writelane_b32 v252, s1, 63
	s_and_saveexec_b64 s[0:1], s[4:5]
	v_readlane_b32 s22, v252, 48
	v_readlane_b32 s23, v252, 49
	s_cbranch_execz .LBB0_948
	s_mov_b64 s[6:7], exec
	v_mbcnt_lo_u32_b32 v2, s6, 0
	v_mbcnt_hi_u32_b32 v2, s7, v2
	v_cmp_eq_u32_e32 vcc, 0, v2
	s_and_saveexec_b64 s[2:3], vcc
	s_cbranch_execz .LBB0_947
	s_bcnt1_i32_b64 s6, s[6:7]
	s_lshl_b32 s6, s6, 1
	v_mov_b32_e32 v4, s6
	v_readlane_b32 s6, v252, 62
	v_mov_b32_e32 v3, 0
	v_readlane_b32 s7, v252, 63
	s_nop 4
	global_atomic_add v3, v3, v4, s[6:7] sc0

; #define LAS __attribute__((address_space(3)))
; __device__ __forceinline__ unsigned xb_ld(unsigned* p)              { return __hip_atomic_load(p, __ATOMIC_RELAXED, __HIP_MEMORY_SCOPE_AGENT); }
; #define XB_SPIN(cond, bar) do { unsigned _sp = 0; while (cond) { __builtin_amdgcn_s_sleep(1); \
;     if ((++_sp & 255u) == 0u) { if (xb_ld(&(bar)[XB_TMO])) break; if (_sp > XB_SPIN_CAP) { atomicAdd(&(bar)[XB_TMO], 1u); break; } } } } while (0)
; __device__ __forceinline__ void p3_scan_and_sb(const Params& P, float* lds) {
;     ...
;     if (blockIdx.x < 96) {
;         const int bh = blockIdx.x >> 2, quarter = blockIdx.x & 3, b = bh / RH, h = bh % RH;
;         volatile LAS unsigned* scw = (volatile LAS unsigned*)((LAS unsigned char*)lds + SC_CTL_OFF);
;         if (tid < 5) scw[tid] = 0u;
;         if (tid == 0) { XB_SPIN(xb_ld(ctl + QW_PREP_W) < (unsigned)NPREP, ctl); __builtin_amdgcn_fence(__ATOMIC_ACQUIRE, "agent"); asm volatile("s_waitcnt vmcnt(0)" ::: "memory"); }
;         __syncthreads();
.LBB0_1203:
	s_and_b64 vcc, exec, s[0:1]
	s_cbranch_vccz .LBB0_1261
	v_cmp_gt_u32_e32 vcc, 5, v0
	s_and_saveexec_b64 s[0:1], vcc
	v_lshl_add_u32 v2, v0, 2, 0
	v_add_u32_e32 v2, 0x23000, v2
	v_mov_b32_e32 v3, 0
	ds_write_b32 v2, v3
	s_or_b64 exec, exec, s[0:1]
	s_and_saveexec_b64 s[0:1], s[80:81]
	s_cbranch_execz .LBB0_1221
	v_mov_b32_e32 v2, 0x3000
	global_load_dword v2, v2, s[78:79] offset:3328 sc1
	s_movk_i32 s10, 0xcf
	s_add_u32 s2, s78, 0x3d00
	s_addc_u32 s3, s79, 0
	s_waitcnt vmcnt(0)
	v_cmp_lt_u32_e32 vcc, s10, v2
	s_cbranch_vccnz .LBB0_1220
	s_mov_b32 s11, 1
	v_mov_b32_e32 v2, 0
	s_branch .LBB0_1210

; __device__ __forceinline__ unsigned xb_ld(unsigned* p)              { return __hip_atomic_load(p, __ATOMIC_RELAXED, __HIP_MEMORY_SCOPE_AGENT); }
; #define XB_SPIN(cond, bar) do { unsigned _sp = 0; while (cond) { __builtin_amdgcn_s_sleep(1); \
;     if ((++_sp & 255u) == 0u) { if (xb_ld(&(bar)[XB_TMO])) break; if (_sp > XB_SPIN_CAP) { atomicAdd(&(bar)[XB_TMO], 1u); break; } } } } while (0)
; __device__ __forceinline__ void p3_scan_and_sb(const Params& P, float* lds) {
;     ...
;     sb_decode_wave_loop(P, lds);
;     if (lane == 0) XB_SPIN(xb_ld(ctl + QW_PREP_W) < (unsigned)NPREP, ctl);
;     __builtin_amdgcn_fence(__ATOMIC_ACQUIRE, "agent");
.LBB0_1555:
	s_and_saveexec_b64 s[0:1], s[4:5]
	v_readlane_b32 s58, v252, 48
	v_readlane_b32 s59, v252, 49
	s_load_dwordx8 s[68:75], s[58:59], 0xc0
	v_readlane_b32 s80, v252, 56
	v_readlane_b32 s60, v252, 51
	v_readlane_b32 s34, v252, 54
	v_readlane_b32 s81, v252, 57
	v_readlane_b32 s56, v252, 53
	v_readlane_b32 s61, v252, 52
	v_readlane_b32 s57, v252, 50
	v_readlane_b32 s35, v252, 55
	s_cbranch_execz .LBB0_1568
	v_mov_b32_e32 v1, 0x3000
	global_load_dword v1, v1, s[78:79] offset:3328 sc1
	s_movk_i32 s10, 0xcf
	s_add_u32 s2, s78, 0x3d00
	s_addc_u32 s3, s79, 0
	s_waitcnt vmcnt(0)
	v_cmp_lt_u32_e32 vcc, s10, v1
	s_cbranch_vccnz .LBB0_1568
	s_mov_b32 s11, 1
	v_mov_b32_e32 v1, 0
	s_branch .LBB0_1559
